# third-round weight-copy items dealt as pairs: waves 0-1 of all 128 conversion workgroups plus waves 2-3 of the first 32
# speedup vs baseline: 1.0027x; 1.0027x over previous
; __device__ __forceinline__ void convert_weights(const Args& args, int first, int last, int worker, int nworkers, int lane) {
;     ...
;     for (;;) {
;         const int nx = it + nworkers; const bool more = nx < last;
;         WItem nxt = cur; f32x4 vn[WR];
;         if (more) { nxt = witem_decode(args, nx, lane); witem_load(nxt, vn); }
;         witem_store(cur, v);
;         if (!more) break;
; #pragma unroll
;         for (int j = 0; j < WR; ++j) v[j] = vn[j];
;         cur = nxt; it = nx;
.LBB0_429:
	s_add_i32 s28, s33, 0x400
	s_cmpk_gt_i32 s33, 0x8ff
	s_cselect_b64 s[8:9], -1, 0
	s_cmpk_lt_i32 s33, 0x7c0
	s_cbranch_scc1 .Lcv3_keep
	s_cmpk_gt_i32 s33, 0xbbf
	s_cbranch_scc1 .Lcv3_keep
	s_add_i32 s98, s33, 0xfffff840
	s_and_b32 s99, s98, 7
	s_lshr_b32 s28, s98, 3
	s_lshl_b32 s28, s28, 1
	s_add_i32 s28, s28, s99
	s_cmp_lt_u32 s99, 2
	s_cbranch_scc1 .Lcv3_ok
	s_addk_i32 s28, 0xfe
	s_cmp_gt_u32 s99, 3
	s_cselect_b32 s99, 1, 0
	s_cmpk_gt_u32 s98, 0xff
	s_cselect_b32 s99, 1, s99
	s_cmp_lg_u32 s99, 0
	s_cselect_b64 s[8:9], -1, 0
	s_branch .Lcv3_fin
.Lcv3_ok:
	s_mov_b64 s[8:9], 0
.Lcv3_fin:
	s_addk_i32 s28, 0xbc0
	s_add_i32 s33, s28, 0xfffffc00
